# stack14: stack10 + idle-tail reuse: layer-1 K-cache conversion done by the spare CUs of layer-0 FFN-up phase tail, V-cache conversion of each layer done by the spare CUs of the input-projection phase
# baseline (speedup 1.0000x reference)
.LBB0_171:
	s_add_u32 s12, s96, 0x16708000
	s_waitcnt lgkmcnt(0)
	s_mov_b32 s2, 0x200000
	s_addc_u32 s13, s97, 0
	v_cmp_gt_i32_e32 vcc, s2, v16
	s_and_saveexec_b64 s[2:3], vcc
	v_readlane_b32 s10, v250, 43
	s_cbranch_execz .LBB0_174
	v_readlane_b32 s100, v250, 58
	s_cmp_eq_u32 s100, 1
	s_cbranch_scc1 .LBB0_174
	s_load_dwordx2 s[6:7], s[26:27], 0x10
	v_readlane_b32 s4, v250, 58
	v_readlane_b32 s5, v250, 59
	s_lshl_b64 s[8:9], s[4:5], 26
	v_lshlrev_b32_e32 v0, 3, v22
	s_waitcnt lgkmcnt(0)
	s_add_u32 s6, s6, s8
	s_mov_b64 s[4:5], 0
	v_lshl_add_u32 v0, s30, 12, v0
	s_addc_u32 s7, s7, s9
	v_mov_b32_e32 v1, v16

.LBB0_589:
	s_cmp_gt_u32 s90, 0xa6
	s_cselect_b32 s39, 0xa6, 0
	s_cmp_lt_u32 s21, s39
	s_cbranch_scc1 .Lvcb_done
	s_sub_u32 s36, s21, s39
	s_lshl_b32 s36, s36, 9
	s_sub_u32 s38, s90, s39
	s_lshl_b32 s38, s38, 9
	v_readlane_b32 s44, v250, 52
	v_readlane_b32 s45, v250, 53
	v_readlane_b32 s37, v250, 58
	s_nop 4
	s_load_dwordx2 s[46:47], s[44:45], 0x18
	s_add_u32 s42, s96, 0x1a788000
	s_addc_u32 s43, s97, 0
	v_add_u32_e32 v0, s36, v224
	s_lshl_b32 s37, s37, 26
	s_waitcnt lgkmcnt(0)
	s_add_u32 s46, s46, s37
	s_addc_u32 s47, s47, 0
.Lvcb_loop:
	v_add_u32_e32 v1, s38, v0
	v_add_u32_e32 v2, s38, v1
	v_add_u32_e32 v3, s38, v2
	v_min_u32_e32 v4, 0x1fffff, v0
	v_lshrrev_b32_e32 v5, 18, v4
	v_bfe_u32 v6, v4, 9, 9
	v_and_b32_e32 v7, 0x1ff, v4
	v_lshlrev_b32_e32 v16, 23, v5
	v_lshl_add_u32 v16, v6, 14, v16
	v_lshl_add_u32 v16, v7, 2, v16
	v_add_u32_e32 v17, 0x1000, v16
	v_add_u32_e32 v18, 0x2000, v16
	v_add_u32_e32 v19, 0x3000, v16
	global_load_dword v32, v16, s[46:47]
	global_load_dword v33, v16, s[46:47] offset:2048
	global_load_dword v34, v17, s[46:47]
	global_load_dword v35, v17, s[46:47] offset:2048
	global_load_dword v36, v18, s[46:47]
	global_load_dword v37, v18, s[46:47] offset:2048
	global_load_dword v38, v19, s[46:47]
	global_load_dword v39, v19, s[46:47] offset:2048
	v_lshl_add_u32 v5, v5, 9, v7
	v_mul_u32_u24_e32 v5, 0x2080, v5
	v_lshl_add_u32 v12, v6, 4, v5
	v_min_u32_e32 v4, 0x1fffff, v1
	v_lshrrev_b32_e32 v5, 18, v4
	v_bfe_u32 v6, v4, 9, 9
	v_and_b32_e32 v7, 0x1ff, v4
	v_lshlrev_b32_e32 v20, 23, v5
	v_lshl_add_u32 v20, v6, 14, v20
	v_lshl_add_u32 v20, v7, 2, v20
	v_add_u32_e32 v21, 0x1000, v20
	v_add_u32_e32 v22, 0x2000, v20
	v_add_u32_e32 v23, 0x3000, v20
	global_load_dword v40, v20, s[46:47]
	global_load_dword v41, v20, s[46:47] offset:2048
	global_load_dword v42, v21, s[46:47]
	global_load_dword v43, v21, s[46:47] offset:2048
	global_load_dword v44, v22, s[46:47]
	global_load_dword v45, v22, s[46:47] offset:2048
	global_load_dword v46, v23, s[46:47]
	global_load_dword v47, v23, s[46:47] offset:2048
	v_lshl_add_u32 v5, v5, 9, v7
	v_mul_u32_u24_e32 v5, 0x2080, v5
	v_lshl_add_u32 v13, v6, 4, v5
	v_min_u32_e32 v4, 0x1fffff, v2
	v_lshrrev_b32_e32 v5, 18, v4
	v_bfe_u32 v6, v4, 9, 9
	v_and_b32_e32 v7, 0x1ff, v4
	v_lshlrev_b32_e32 v24, 23, v5
	v_lshl_add_u32 v24, v6, 14, v24
	v_lshl_add_u32 v24, v7, 2, v24
	v_add_u32_e32 v25, 0x1000, v24
	v_add_u32_e32 v26, 0x2000, v24
	v_add_u32_e32 v27, 0x3000, v24
	global_load_dword v48, v24, s[46:47]
	global_load_dword v49, v24, s[46:47] offset:2048
	global_load_dword v50, v25, s[46:47]
	global_load_dword v51, v25, s[46:47] offset:2048
	global_load_dword v52, v26, s[46:47]
	global_load_dword v53, v26, s[46:47] offset:2048
	global_load_dword v54, v27, s[46:47]
	global_load_dword v55, v27, s[46:47] offset:2048
	v_lshl_add_u32 v5, v5, 9, v7
	v_mul_u32_u24_e32 v5, 0x2080, v5
	v_lshl_add_u32 v14, v6, 4, v5
	v_min_u32_e32 v4, 0x1fffff, v3
	v_lshrrev_b32_e32 v5, 18, v4
	v_bfe_u32 v6, v4, 9, 9
	v_and_b32_e32 v7, 0x1ff, v4
	v_lshlrev_b32_e32 v28, 23, v5
	v_lshl_add_u32 v28, v6, 14, v28
	v_lshl_add_u32 v28, v7, 2, v28
	v_add_u32_e32 v29, 0x1000, v28
	v_add_u32_e32 v30, 0x2000, v28
	v_add_u32_e32 v31, 0x3000, v28
	global_load_dword v56, v28, s[46:47]
	global_load_dword v57, v28, s[46:47] offset:2048
	global_load_dword v58, v29, s[46:47]
	global_load_dword v59, v29, s[46:47] offset:2048
	global_load_dword v60, v30, s[46:47]
	global_load_dword v61, v30, s[46:47] offset:2048
	global_load_dword v62, v31, s[46:47]
	global_load_dword v63, v31, s[46:47] offset:2048
	v_lshl_add_u32 v5, v5, 9, v7
	v_mul_u32_u24_e32 v5, 0x2080, v5
	v_lshl_add_u32 v15, v6, 4, v5
	s_waitcnt vmcnt(24)
	v_cvt_pk_bf16_f32 v32, v32, v33
	v_cvt_pk_bf16_f32 v33, v34, v35
	v_cvt_pk_bf16_f32 v34, v36, v37
	v_cvt_pk_bf16_f32 v35, v38, v39
	v_cmp_gt_u32_e32 vcc, 0x200000, v0
	s_and_saveexec_b64 s[44:45], vcc
	global_store_dwordx4 v12, v[32:35], s[42:43]
	s_mov_b64 exec, s[44:45]
	s_waitcnt vmcnt(16)
	v_cvt_pk_bf16_f32 v40, v40, v41
	v_cvt_pk_bf16_f32 v41, v42, v43
	v_cvt_pk_bf16_f32 v42, v44, v45
	v_cvt_pk_bf16_f32 v43, v46, v47
	v_cmp_gt_u32_e32 vcc, 0x200000, v1
	s_and_saveexec_b64 s[44:45], vcc
	global_store_dwordx4 v13, v[40:43], s[42:43]
	s_mov_b64 exec, s[44:45]
	s_waitcnt vmcnt(8)
	v_cvt_pk_bf16_f32 v48, v48, v49
	v_cvt_pk_bf16_f32 v49, v50, v51
	v_cvt_pk_bf16_f32 v50, v52, v53
	v_cvt_pk_bf16_f32 v51, v54, v55
	v_cmp_gt_u32_e32 vcc, 0x200000, v2
	s_and_saveexec_b64 s[44:45], vcc
	global_store_dwordx4 v14, v[48:51], s[42:43]
	s_mov_b64 exec, s[44:45]
	s_waitcnt vmcnt(0)
	v_cvt_pk_bf16_f32 v56, v56, v57
	v_cvt_pk_bf16_f32 v57, v58, v59
	v_cvt_pk_bf16_f32 v58, v60, v61
	v_cvt_pk_bf16_f32 v59, v62, v63
	v_cmp_gt_u32_e32 vcc, 0x200000, v3
	s_and_saveexec_b64 s[44:45], vcc
	global_store_dwordx4 v15, v[56:59], s[42:43]
	s_mov_b64 exec, s[44:45]
	v_add_u32_e32 v0, s38, v3
	s_nop 1
	v_readfirstlane_b32 s36, v0
	s_cmp_lt_u32 s36, 0x200000
	s_cbranch_scc1 .Lvcb_loop

.LBB0_1634:
	v_readlane_b32 s101, v250, 58
	s_cmp_lg_u32 s101, 0
	s_cbranch_scc1 .Lkvh_done
	s_cmp_gt_u32 s90, 44
	s_cselect_b32 s100, 44, 0
	s_cmp_lt_u32 s21, s100
	s_cbranch_scc1 .Lkvh_done
	s_sub_u32 s101, s21, s100
	s_lshl_b32 s101, s101, 9
	s_sub_u32 s49, s90, s100
	s_lshl_b32 s49, s49, 9
	v_readlane_b32 s44, v250, 52
	v_readlane_b32 s45, v250, 53
	s_nop 4
	s_load_dwordx2 s[46:47], s[44:45], 0x10
	s_add_u32 s42, s96, 0x16708000
	s_addc_u32 s43, s97, 0
	v_add_u32_e32 v0, s101, v224
	s_waitcnt lgkmcnt(0)
	s_add_u32 s46, s46, 0x4000000
	s_addc_u32 s47, s47, 0
.Lkvh_kloop:
	v_add_u32_e32 v1, s49, v0
	v_add_u32_e32 v2, s49, v1
	v_add_u32_e32 v3, s49, v2
	v_min_u32_e32 v4, 0x1fffff, v0
	v_lshlrev_b32_e32 v4, 5, v4
	v_min_u32_e32 v5, 0x1fffff, v1
	v_lshlrev_b32_e32 v5, 5, v5
	v_min_u32_e32 v6, 0x1fffff, v2
	v_lshlrev_b32_e32 v6, 5, v6
	v_min_u32_e32 v7, 0x1fffff, v3
	v_lshlrev_b32_e32 v7, 5, v7
	global_load_dwordx4 v[32:35], v4, s[46:47]
	global_load_dwordx4 v[36:39], v4, s[46:47] offset:16
	global_load_dwordx4 v[40:43], v5, s[46:47]
	global_load_dwordx4 v[44:47], v5, s[46:47] offset:16
	global_load_dwordx4 v[48:51], v6, s[46:47]
	global_load_dwordx4 v[52:55], v6, s[46:47] offset:16
	global_load_dwordx4 v[56:59], v7, s[46:47]
	global_load_dwordx4 v[60:63], v7, s[46:47] offset:16
	v_lshrrev_b32_e32 v8, 6, v0
	v_lshrrev_b32_e32 v9, 18, v0
	v_lshl_add_u32 v8, v9, 6, v8
	v_and_b32_e32 v9, 63, v0
	v_lshlrev_b32_e32 v9, 4, v9
	v_lshl_add_u32 v12, v8, 10, v9
	v_lshrrev_b32_e32 v8, 6, v1
	v_lshrrev_b32_e32 v9, 18, v1
	v_lshl_add_u32 v8, v9, 6, v8
	v_and_b32_e32 v9, 63, v1
	v_lshlrev_b32_e32 v9, 4, v9
	v_lshl_add_u32 v13, v8, 10, v9
	v_lshrrev_b32_e32 v8, 6, v2
	v_lshrrev_b32_e32 v9, 18, v2
	v_lshl_add_u32 v8, v9, 6, v8
	v_and_b32_e32 v9, 63, v2
	v_lshlrev_b32_e32 v9, 4, v9
	v_lshl_add_u32 v14, v8, 10, v9
	v_lshrrev_b32_e32 v8, 6, v3
	v_lshrrev_b32_e32 v9, 18, v3
	v_lshl_add_u32 v8, v9, 6, v8
	v_and_b32_e32 v9, 63, v3
	v_lshlrev_b32_e32 v9, 4, v9
	v_lshl_add_u32 v15, v8, 10, v9
	s_waitcnt vmcnt(6)
	v_cvt_pk_bf16_f32 v32, v32, v33
	v_cvt_pk_bf16_f32 v33, v34, v35
	v_cvt_pk_bf16_f32 v34, v36, v37
	v_cvt_pk_bf16_f32 v35, v38, v39
	v_cmp_gt_u32_e32 vcc, 0x200000, v0
	s_and_saveexec_b64 s[44:45], vcc
	global_store_dwordx4 v12, v[32:35], s[42:43]
	s_mov_b64 exec, s[44:45]
	s_waitcnt vmcnt(4)
	v_cvt_pk_bf16_f32 v40, v40, v41
	v_cvt_pk_bf16_f32 v41, v42, v43
	v_cvt_pk_bf16_f32 v42, v44, v45
	v_cvt_pk_bf16_f32 v43, v46, v47
	v_cmp_gt_u32_e32 vcc, 0x200000, v1
	s_and_saveexec_b64 s[44:45], vcc
	global_store_dwordx4 v13, v[40:43], s[42:43]
	s_mov_b64 exec, s[44:45]
	s_waitcnt vmcnt(2)
	v_cvt_pk_bf16_f32 v48, v48, v49
	v_cvt_pk_bf16_f32 v49, v50, v51
	v_cvt_pk_bf16_f32 v50, v52, v53
	v_cvt_pk_bf16_f32 v51, v54, v55
	v_cmp_gt_u32_e32 vcc, 0x200000, v2
	s_and_saveexec_b64 s[44:45], vcc
	global_store_dwordx4 v14, v[48:51], s[42:43]
	s_mov_b64 exec, s[44:45]
	s_waitcnt vmcnt(0)
	v_cvt_pk_bf16_f32 v56, v56, v57
	v_cvt_pk_bf16_f32 v57, v58, v59
	v_cvt_pk_bf16_f32 v58, v60, v61
	v_cvt_pk_bf16_f32 v59, v62, v63
	v_cmp_gt_u32_e32 vcc, 0x200000, v3
	s_and_saveexec_b64 s[44:45], vcc
	global_store_dwordx4 v15, v[56:59], s[42:43]
	s_mov_b64 exec, s[44:45]
	v_add_u32_e32 v0, s49, v3
	s_nop 1
	v_readfirstlane_b32 s101, v0
	s_cmp_lt_u32 s101, 0x200000
	s_cbranch_scc1 .Lkvh_kloop
